# quad-level (4 workgroups sharing pm) sync at the nine GEMM->GEMM seams; group counter still bumped for deferred overlay checks (now incl. own group)
# baseline (speedup 1.0000x reference)
.Llb_tab:
	s_lshl_b32 s15, s8, 3
	s_lshr_b64 s[16:17], s[16:17], s15
	s_and_b32 s16, s16, 0xff
	s_lshl_b32 s16, s16, 16
	s_or_b32 s99, s16, s9
.Llb_have:
	global_atomic_add v2, v1, s[10:11]
	s_mov_b32 s16, 0x19f3
	s_lshr_b32 s17, s16, s6
	s_and_b32 s17, s17, 1
	s_cmp_eq_u32 s17, 0
	s_cbranch_scc1 .Llb_grp
	s_lshl_b32 s17, 2, s6
	s_sub_i32 s17, s17, 1
	s_and_b32 s17, s17, s16
	s_bcnt1_i32_b32 s17, s17
	s_lshl_b32 s15, s17, 2
	v_readlane_b32 s17, v252, 0
	s_nop 0
	s_and_b32 s17, s17, 63
	s_lshl_b32 s17, s17, 4
	s_add_i32 s17, s17, 0x500
	v_mov_b32_e32 v2, s17
	s_nop 0
	global_atomic_add v2, v1, s[10:11]
	s_mov_b32 s13, 0x100
	s_branch .Llb_pollsetup
.Llb_grp:
	s_mov_b32 s17, 0x300
	s_mov_b32 s15, 0
	s_branch .Llb_pollsetup
